# selection slow path rewritten: padded T5-bias LUT read with ds_read2_b32 per 4 keys, in-place mask/bias, shared exp/PV tail with fast path
# baseline (speedup 1.0000x reference)
; #define LAS __attribute__((address_space(3)))
; __device__ __forceinline__ void nsa_unit(const Params& p, int bg, int jq, LAS unsigned char* lds, int wave, int lane, bool build_lut) {
;     ...
;     if (build_lut) {
;         for (int e = lane; e < 4 * 129; e += 64) {
;             const int rr = e / 129, n = e % 129;
;             int bk = n;
;             if (n >= 16) bk = 16 + (n >= 19) + (n >= 21) + (n >= 24) + (n >= 27) + (n >= 31) + (n >= 35) + (n >= 40) + (n >= 46) + (n >= 52) + (n >= 59) + (n >= 67) + (n >= 77) + (n >= 87) + (n >= 99) + (n >= 113);
;             lut[rr * 132 + n] = relb[bk * 8 + g * 4 + rr] * LOG2E;
;         }
;     }
; #pragma unroll
;     for (int e = 0; e < 8; ++e) *(LAS f32x4*)(imp + 4 * (lane + 64 * e)) = (f32x4){0.f, 0.f, 0.f, 0.f};
;     {
;         const int k = lane & 7; unsigned w = 0u;
;         if (k == 0) w |= 1u;
;         if ((jq >> 5) == k) w |= 1u << (jq & 31);
;         if (jq >= 1 && ((jq - 1) >> 5) == k) w |= 1u << ((jq - 1) & 31);
;         selw[lane] = w;
;     }
;     asm volatile("s_waitcnt lgkmcnt(0)" ::: "memory");
;     __builtin_amdgcn_wave_barrier();
;     const LAS float* lutr = lut + r * 132;
;     const float lutfar = lutr[128];
;     bf16x8 qf[4];
; #pragma unroll
;     for (int ks = 0; ks < 4; ++ks) qf[ks] = *(const bf16x8*)(qb + tok * 512 + (g * 4 + r) * 64 + ks * 16 + h * 8);
;     const float g0 = gates[tok * 24 + (g * 4 + r) * 3 + 0], g1 = gates[tok * 24 + (g * 4 + r) * 3 + 1], g2 = gates[tok * 24 + (g * 4 + r) * 3 + 2];
.LBB0_1051:
	s_or_b64 exec, exec, s[4:5]
	s_lshl_b32 s4, s26, 6
	s_and_b32 s28, s4, 0xffffe000
	s_lshl_b32 s4, s27, 6
	s_and_b32 s4, s4, 0x80
	s_bitcmp0_b32 s27, 0
	v_readlane_b32 s5, v253, 17
	v_readlane_b32 s6, v253, 18
	s_cselect_b32 s29, s5, s6
	s_add_i32 s20, s29, s4
	s_waitcnt lgkmcnt(0)
	s_add_u32 s16, s14, 0xa900000
	s_addc_u32 s17, s15, 0
	v_readlane_b32 s4, v253, 56
	s_add_u32 s4, s14, s4
	s_addc_u32 s5, s15, 0
	s_add_u32 s6, s4, 0x14300000
	s_addc_u32 s7, s5, 0
	s_lshl_b32 s4, s20, 6
	s_lshl_b32 s30, s12, 3
	v_bfe_u32 v158, v145, 2, 3
	s_add_i32 s31, s30, s4
	s_add_i32 s34, s18, 0
	v_or_b32_e32 v2, s31, v158
	s_ashr_i32 s8, s20, 5
	s_lshl_b32 s9, 1, s29
	v_ashrrev_i32_e32 v3, 31, v2
	v_and_b32_e32 v118, 7, v145
	s_cmp_gt_i32 s20, 0
	v_lshl_add_u64 v[182:183], v[2:3], 0, s[90:91]
	s_mov_b32 s73, s72
	v_mov_b32_e32 v3, s9
	v_cmp_eq_u32_e32 vcc, s8, v118
	s_cselect_b64 s[8:9], -1, 0
	s_add_i32 s10, s20, -1
	v_lshlrev_b32_e32 v114, 4, v145
	s_mov_b32 s74, s72
	s_mov_b32 s75, s72
	v_mov_b64_e32 v[4:5], s[72:73]
	s_lshr_b32 s11, s10, 5
	v_add_u32_e32 v2, s34, v114
	v_mov_b64_e32 v[6:7], s[74:75]
	v_cndmask_b32_e32 v3, 0, v3, vcc
	v_cmp_eq_u32_e32 vcc, s11, v118
	s_lshl_b32 s10, 1, s10
	ds_write_b128 v2, v[4:7]
	ds_write_b128 v2, v[4:7] offset:1024
	ds_write_b128 v2, v[4:7] offset:2048
	ds_write_b128 v2, v[4:7] offset:3072
	ds_write_b128 v2, v[4:7] offset:4096
	ds_write_b128 v2, v[4:7] offset:5120
	ds_write_b128 v2, v[4:7] offset:6144
	ds_write_b128 v2, v[4:7] offset:7168
	v_cmp_eq_u32_e64 s[4:5], 0, v118
	v_mov_b32_e32 v4, s10
	s_and_b64 vcc, s[8:9], vcc
	v_cndmask_b32_e64 v2, 0, 1, s[4:5]
	v_cndmask_b32_e32 v4, 0, v4, vcc
	v_or3_b32 v2, v3, v2, v4
	v_lshl_add_u32 v159, v145, 2, s34
	v_ashrrev_i32_e32 v179, 5, v145
	v_and_b32_e32 v1, 3, v145
	ds_write_b32 v159, v2 offset:8192
	v_and_b32_e32 v238, 3, v145
	v_mul_u32_u24_e32 v238, 0x210, v238
	v_add_u32_e32 v238, s34, v238
	ds_read_b32 v239, v238 offset:8960
	v_bfe_u32 v240, v145, 2, 2
	v_min_u32_e32 v240, 2, v240
	v_lshl_add_u32 v238, v240, 2, v238
	s_waitcnt lgkmcnt(0)
	ds_write_b32 v238, v239 offset:8964
	v_lshlrev_b64 v[2:3], 10, v[182:183]
	v_readlane_b32 s8, v253, 57
	v_lshl_add_u64 v[140:141], s[16:17], 0, v[2:3]
	v_mov_b32_e32 v3, v0
	v_lshl_or_b32 v2, v1, 7, s8
	v_lshlrev_b32_e32 v142, 3, v179
	v_lshl_add_u64 v[2:3], v[140:141], 0, v[2:3]
	v_ashrrev_i32_e32 v143, 31, v142
	v_lshl_add_u64 v[2:3], v[142:143], 1, v[2:3]
	s_waitcnt lgkmcnt(0)
	global_load_dwordx4 v[66:69], v[2:3], off
	global_load_dwordx4 v[70:73], v[2:3], off offset:32
	global_load_dwordx4 v[74:77], v[2:3], off offset:64
	global_load_dwordx4 v[78:81], v[2:3], off offset:96
	v_or_b32_e32 v115, s3, v1
	v_mov_b64_e32 v[2:3], s[14:15]
	s_movk_i32 s10, 0x60
	v_mul_u32_u24_e32 v4, 3, v115
	v_mad_u64_u32 v[2:3], s[8:9], v182, s10, v[2:3]
	v_mad_i32_i24 v3, v183, s10, v3
	v_lshlrev_b32_e32 v4, 2, v4
	v_mov_b32_e32 v5, v0
	v_lshl_add_u64 v[2:3], v[2:3], 0, v[4:5]
	v_add_co_u32_e32 v2, vcc, 0x13b00000, v2
	s_movk_i32 s8, 0x210
	s_nop 0
	v_addc_co_u32_e32 v3, vcc, 0, v3, vcc
	global_load_dwordx3 v[176:178], v[2:3], off
	v_mov_b32_e32 v2, s34
	v_mad_u32_u24 v231, v1, s8, v2
	s_sub_i32 s8, s31, 24
	s_lshr_b32 s8, s8, 9
	ds_read_b32 v184, v231 offset:8960
	s_add_i32 s12, s8, 1
	s_cmp_gt_i32 s31, 23
	s_cselect_b64 s[8:9], -1, 0
	s_and_b64 s[10:11], s[8:9], exec
	s_cselect_b32 s21, s12, 0
	s_cmp_lt_i32 s31, 24
	s_cbranch_scc1 .LBB0_1092
	v_lshlrev_b32_e32 v2, 3, v145
	v_ashrrev_i32_e32 v3, 31, v2
	v_lshlrev_b64 v[18:19], 1, v[2:3]
	v_lshl_add_u64 v[14:15], s[6:7], 0, v[18:19]
	global_load_dwordx4 v[2:5], v[14:15], off
	global_load_dwordx4 v[6:9], v[14:15], off offset:1024
	global_load_dwordx4 v[10:13], v[14:15], off offset:2048
	s_nop 0
	global_load_dwordx4 v[14:17], v[14:15], off offset:3072
	s_lshl_b32 s10, s29, 6
	s_add_i32 s10, s28, s10
	s_add_i32 s11, s10, s30
	s_sub_i32 s11, s11, 24
	s_lshr_b32 s12, s11, 9
	v_add_u32_e32 v21, s10, v158
	s_sub_i32 s13, s10, 31
	v_readlane_b32 s10, v253, 52
	s_add_u32 s10, s14, s10
	v_lshlrev_b32_e32 v20, 6, v179
	s_addc_u32 s11, s15, 0
	s_waitcnt lgkmcnt(0)
	v_mov_b32_e32 v185, v184
	s_waitcnt vmcnt(9)
	v_mov_b32_e32 v50, v184
	v_mov_b32_e32 v51, v184
	v_mov_b32_e32 v52, v184
	v_mov_b32_e32 v53, v184
	v_mov_b32_e32 v54, v184
	v_mov_b32_e32 v55, v184
	v_mov_b32_e32 v56, v184
	v_mov_b32_e32 v57, v184
	v_mov_b32_e32 v58, v184
	v_mov_b32_e32 v59, v184
	v_mov_b32_e32 v60, v184
	v_mov_b32_e32 v61, v184
	v_mov_b32_e32 v62, v184
	v_mov_b32_e32 v63, v184
	v_sub_u32_e32 v82, v21, v20
	v_lshl_add_u64 v[64:65], s[10:11], 0, v[18:19]
	v_mov_b32_e32 v83, 0
	v_mov_b32_e32 v84, 0xf149f2ca
	s_mov_b32 s19, -1
	s_waitcnt vmcnt(3)
	v_mov_b64_e32 v[36:37], v[4:5]
	s_waitcnt vmcnt(2)
	v_mov_b64_e32 v[40:41], v[8:9]
	s_waitcnt vmcnt(1)
	v_mov_b64_e32 v[44:45], v[12:13]
	s_waitcnt vmcnt(0)
	v_mov_b64_e32 v[48:49], v[16:17]
	v_mov_b64_e32 v[34:35], v[2:3]
	v_mov_b64_e32 v[38:39], v[6:7]
	v_mov_b64_e32 v[42:43], v[10:11]
	v_mov_b64_e32 v[46:47], v[14:15]
	s_add_i32 s10, s19, 2
	s_cmp_lt_u32 s10, s21
	s_cbranch_scc0 .LBB0_1055
	s_branch .LBB0_1054

; __device__ __forceinline__ float fast_exp2(float x) { return __builtin_amdgcn_exp2f(x); }
; __device__ __forceinline__ float xhalf_max(float x) { auto t = __builtin_amdgcn_permlane32_swap(__float_as_uint(x), __float_as_uint(x), false, false); return fmaxf(__uint_as_float(t[0]), __uint_as_float(t[1])); }
; __device__ __forceinline__ void nsa_unit(const Params& p, int bg, int jq, LAS unsigned char* lds, int wave, int lane, bool build_lut) {
;     ...
;                     float mx = NEG_INF;
; #pragma unroll
;                     for (int u = 0; u < 2; ++u)
; #pragma unroll
;                         for (int kt = 0; kt < 4; ++kt)
; #pragma unroll
;                             for (int e = 0; e < 4; ++e) {
;                                 const int d = tqg - 64 * nb[u] - 16 * kt - 4 * fq - e;
;                                 const bool okk = ok[u] && d >= 0;
;                                 const float v = okk ? (sc[u][kt][e] + lutr16[min(max(d, 0), 128)]) : NEG_INF;
;                                 sc[u][kt][e] = v; mx = fmaxf(mx, v);
;                             }
;                     { auto t1 = __builtin_amdgcn_permlane16_swap(__float_as_uint(mx), __float_as_uint(mx), false, false); mx = fmaxf(__uint_as_float(t1[0]), __uint_as_float(t1[1])); mx = xhalf_max(mx); }
;                     if (__any(mx > m + 2.0f)) {
;                         const float mnew = (mx > m + 2.0f) ? mx : m;
;                         const float alpha = fast_exp2(m - mnew);
;                         lacc = lacc * alpha; m = mnew;
; #pragma unroll
;                         for (int dt = 0; dt < 4; ++dt) o[dt] = o[dt] * alpha;
;                     }
.LBB0_1204:
	s_andn2_b64 vcc, exec, s[24:25]
	s_mov_b64 s[24:25], -1
	s_cbranch_vccnz .Lsel_fast
	s_lshl_b32 s9, s22, 6
	s_lshl_b32 s8, s8, 6
	v_mov_b32_e32 v240, 0xff800000
	v_mov_b32_e32 v2, 0x7fffffff
	v_mov_b32_e32 v3, s9
	v_cndmask_b32_e64 v232, v2, v3, s[6:7]
	v_mov_b32_e32 v3, s8
	v_cndmask_b32_e64 v233, v2, v3, s[20:21]
	v_add_u32_e32 v1, 0x20f4, v231
	v_subrev_u32_e32 v192, s9, v168
	v_min_u32_e32 v192, 0x83, v192
	v_lshl_add_u32 v192, v192, 2, v1
	ds_read2_b32 v[194:195], v192 offset0:1 offset1:0
	ds_read2_b32 v[192:193], v192 offset0:3 offset1:2
	v_subrev_u32_e32 v196, s9, v172
	v_min_u32_e32 v196, 0x83, v196
	v_lshl_add_u32 v196, v196, 2, v1
	ds_read2_b32 v[198:199], v196 offset0:1 offset1:0
	ds_read2_b32 v[196:197], v196 offset0:3 offset1:2
	v_subrev_u32_e32 v200, s9, v176
	v_min_u32_e32 v200, 0x83, v200
	v_lshl_add_u32 v200, v200, 2, v1
	ds_read2_b32 v[202:203], v200 offset0:1 offset1:0
	ds_read2_b32 v[200:201], v200 offset0:3 offset1:2
	v_subrev_u32_e32 v204, s9, v188
	v_min_u32_e32 v204, 0x83, v204
	v_lshl_add_u32 v204, v204, 2, v1
	ds_read2_b32 v[206:207], v204 offset0:1 offset1:0
	ds_read2_b32 v[204:205], v204 offset0:3 offset1:2
	v_subrev_u32_e32 v208, s8, v168
	v_min_u32_e32 v208, 0x83, v208
	v_lshl_add_u32 v208, v208, 2, v1
	ds_read2_b32 v[210:211], v208 offset0:1 offset1:0
	ds_read2_b32 v[208:209], v208 offset0:3 offset1:2
	v_subrev_u32_e32 v212, s8, v172
	v_min_u32_e32 v212, 0x83, v212
	v_lshl_add_u32 v212, v212, 2, v1
	ds_read2_b32 v[214:215], v212 offset0:1 offset1:0
	ds_read2_b32 v[212:213], v212 offset0:3 offset1:2
	v_subrev_u32_e32 v216, s8, v176
	v_min_u32_e32 v216, 0x83, v216
	v_lshl_add_u32 v216, v216, 2, v1
	ds_read2_b32 v[218:219], v216 offset0:1 offset1:0
	ds_read2_b32 v[216:217], v216 offset0:3 offset1:2
	v_subrev_u32_e32 v124, s8, v188
	v_min_u32_e32 v124, 0x83, v124
	v_lshl_add_u32 v124, v124, 2, v1
	ds_read2_b32 v[126:127], v124 offset0:1 offset1:0
	ds_read2_b32 v[124:125], v124 offset0:3 offset1:2
	s_waitcnt lgkmcnt(14)
	v_cmp_ge_i32_e32 vcc, v168, v232
	v_cmp_ge_i32_e64 s[46:47], v169, v232
	v_add_f32_e32 v116, v116, v192
	v_add_f32_e32 v117, v117, v193
	v_cndmask_b32_e32 v116, v240, v116, vcc
	v_cndmask_b32_e64 v117, v240, v117, s[46:47]
	v_cmp_ge_i32_e32 vcc, v170, v232
	v_cmp_ge_i32_e64 s[46:47], v171, v232
	v_add_f32_e32 v118, v118, v194
	v_add_f32_e32 v119, v119, v195
	v_cndmask_b32_e32 v118, v240, v118, vcc
	v_cndmask_b32_e64 v119, v240, v119, s[46:47]
	s_waitcnt lgkmcnt(12)
	v_cmp_ge_i32_e32 vcc, v172, v232
	v_cmp_ge_i32_e64 s[46:47], v173, v232
	v_add_f32_e32 v108, v108, v196
	v_add_f32_e32 v109, v109, v197
	v_cndmask_b32_e32 v108, v240, v108, vcc
	v_cndmask_b32_e64 v109, v240, v109, s[46:47]
	v_cmp_ge_i32_e32 vcc, v174, v232
	v_cmp_ge_i32_e64 s[46:47], v175, v232
	v_add_f32_e32 v110, v110, v198
	v_add_f32_e32 v111, v111, v199
	v_cndmask_b32_e32 v110, v240, v110, vcc
	v_cndmask_b32_e64 v111, v240, v111, s[46:47]
	s_waitcnt lgkmcnt(10)
	v_cmp_ge_i32_e32 vcc, v176, v232
	v_cmp_ge_i32_e64 s[46:47], v185, v232
	v_add_f32_e32 v96, v96, v200
	v_add_f32_e32 v97, v97, v201
	v_cndmask_b32_e32 v96, v240, v96, vcc
	v_cndmask_b32_e64 v97, v240, v97, s[46:47]
	v_cmp_ge_i32_e32 vcc, v186, v232
	v_cmp_ge_i32_e64 s[46:47], v187, v232
	v_add_f32_e32 v98, v98, v202
	v_add_f32_e32 v99, v99, v203
	v_cndmask_b32_e32 v98, v240, v98, vcc
	v_cndmask_b32_e64 v99, v240, v99, s[46:47]
	s_waitcnt lgkmcnt(8)
	v_cmp_ge_i32_e32 vcc, v188, v232
	v_cmp_ge_i32_e64 s[46:47], v189, v232
	v_add_f32_e32 v100, v100, v204
	v_add_f32_e32 v101, v101, v205
	v_cndmask_b32_e32 v100, v240, v100, vcc
	v_cndmask_b32_e64 v101, v240, v101, s[46:47]
	v_cmp_ge_i32_e32 vcc, v190, v232
	v_cmp_ge_i32_e64 s[46:47], v191, v232
	v_add_f32_e32 v102, v102, v206
	v_add_f32_e32 v103, v103, v207
	v_cndmask_b32_e32 v102, v240, v102, vcc
	v_cndmask_b32_e64 v103, v240, v103, s[46:47]
	s_waitcnt lgkmcnt(6)
	v_cmp_ge_i32_e32 vcc, v168, v233
	v_cmp_ge_i32_e64 s[46:47], v169, v233
	v_add_f32_e32 v112, v112, v208
	v_add_f32_e32 v113, v113, v209
	v_cndmask_b32_e32 v112, v240, v112, vcc
	v_cndmask_b32_e64 v113, v240, v113, s[46:47]
	v_cmp_ge_i32_e32 vcc, v170, v233
	v_cmp_ge_i32_e64 s[46:47], v171, v233
	v_add_f32_e32 v114, v114, v210
	v_add_f32_e32 v115, v115, v211
	v_cndmask_b32_e32 v114, v240, v114, vcc
	v_cndmask_b32_e64 v115, v240, v115, s[46:47]
	s_waitcnt lgkmcnt(4)
	v_cmp_ge_i32_e32 vcc, v172, v233
	v_cmp_ge_i32_e64 s[46:47], v173, v233
	v_add_f32_e32 v104, v104, v212
	v_add_f32_e32 v105, v105, v213
	v_cndmask_b32_e32 v104, v240, v104, vcc
	v_cndmask_b32_e64 v105, v240, v105, s[46:47]
	v_cmp_ge_i32_e32 vcc, v174, v233
	v_cmp_ge_i32_e64 s[46:47], v175, v233
	v_add_f32_e32 v106, v106, v214
	v_add_f32_e32 v107, v107, v215
	v_cndmask_b32_e32 v106, v240, v106, vcc
	v_cndmask_b32_e64 v107, v240, v107, s[46:47]
	s_waitcnt lgkmcnt(2)
	v_cmp_ge_i32_e32 vcc, v176, v233
	v_cmp_ge_i32_e64 s[46:47], v185, v233
	v_add_f32_e32 v92, v92, v216
	v_add_f32_e32 v93, v93, v217
	v_cndmask_b32_e32 v92, v240, v92, vcc
	v_cndmask_b32_e64 v93, v240, v93, s[46:47]
	v_cmp_ge_i32_e32 vcc, v186, v233
	v_cmp_ge_i32_e64 s[46:47], v187, v233
	v_add_f32_e32 v94, v94, v218
	v_add_f32_e32 v95, v95, v219
	v_cndmask_b32_e32 v94, v240, v94, vcc
	v_cndmask_b32_e64 v95, v240, v95, s[46:47]
	s_waitcnt lgkmcnt(0)
	v_cmp_ge_i32_e32 vcc, v188, v233
	v_cmp_ge_i32_e64 s[46:47], v189, v233
	v_add_f32_e32 v88, v88, v124
	v_add_f32_e32 v89, v89, v125
	v_cndmask_b32_e32 v88, v240, v88, vcc
	v_cndmask_b32_e64 v89, v240, v89, s[46:47]
	v_cmp_ge_i32_e32 vcc, v190, v233
	v_cmp_ge_i32_e64 s[46:47], v191, v233
	v_add_f32_e32 v90, v90, v126
	v_add_f32_e32 v91, v91, v127
	v_cndmask_b32_e32 v90, v240, v90, vcc
	v_cndmask_b32_e64 v91, v240, v91, s[46:47]
	v_max3_f32 v1, v116, v117, v118
	v_max3_f32 v2, v119, v108, v109
	v_max3_f32 v3, v110, v111, v100
	v_max3_f32 v120, v101, v102, v103
	v_max3_f32 v121, v112, v113, v114
	v_max3_f32 v122, v115, v104, v105
	v_max3_f32 v123, v106, v107, v96
	v_max3_f32 v1, v1, v97, v98
	v_max3_f32 v2, v2, v99, v92
	v_max3_f32 v3, v3, v93, v94
	v_max3_f32 v120, v120, v95, v88
	v_max3_f32 v121, v121, v89, v90
	v_max3_f32 v122, v122, v91, v123
	v_max3_f32 v1, v1, v2, v3
	v_max3_f32 v120, v120, v121, v122
	v_max_f32_e32 v1, v1, v120
	v_mov_b32_e32 v2, v1
	s_nop 1
	v_permlane16_swap_b32_e32 v1, v2
	v_max_f32_e32 v1, v1, v2
	v_mov_b32_e32 v2, v1
	s_nop 1
	v_permlane32_swap_b32_e32 v1, v2
	v_max_f32_e32 v1, v1, v2
	v_add_f32_e32 v2, 2.0, v157
	v_cmp_gt_f32_e32 vcc, v1, v2
	s_nop 1
	s_cbranch_vccz .Lslow_nors
; __device__ __forceinline__ float fast_exp2(float x) { return __builtin_amdgcn_exp2f(x); }
; __device__ __forceinline__ void nsa_unit(const Params& p, int bg, int jq, LAS unsigned char* lds, int wave, int lane, bool build_lut) {
;     ...
;                     if (__any(mx > m + 2.0f)) {
;                         const float mnew = (mx > m + 2.0f) ? mx : m;
;                         const float alpha = fast_exp2(m - mnew);
;                         lacc = lacc * alpha; m = mnew;
; #pragma unroll
;                         for (int dt = 0; dt < 4; ++dt) o[dt] = o[dt] * alpha;
;                     }
;                     const float cexp = m - 6.0f;
; #pragma unroll
;                     for (int u = 0; u < 2; ++u)
; #pragma unroll
;                         for (int kt = 0; kt < 4; ++kt)
; #pragma unroll
;                             for (int e = 0; e < 4; ++e) sc[u][kt][e] = fast_exp2(sc[u][kt][e] - cexp);
	s_nop 0
	v_cndmask_b32_e32 v3, v157, v1, vcc
	v_sub_f32_e32 v2, v157, v3
	v_exp_f32_e32 v2, v2
	v_mov_b32_e32 v157, v3
	s_nop 0
	v_pk_mul_f32 v[50:51], v[50:51], v[2:3] op_sel_hi:[1,0]
	v_pk_mul_f32 v[48:49], v[48:49], v[2:3] op_sel_hi:[1,0]
	v_pk_mul_f32 v[46:47], v[46:47], v[2:3] op_sel_hi:[1,0]
	v_pk_mul_f32 v[44:45], v[44:45], v[2:3] op_sel_hi:[1,0]
	v_pk_mul_f32 v[42:43], v[42:43], v[2:3] op_sel_hi:[1,0]
	v_pk_mul_f32 v[40:41], v[40:41], v[2:3] op_sel_hi:[1,0]
	v_pk_mul_f32 v[26:27], v[26:27], v[2:3] op_sel_hi:[1,0]
	v_pk_mul_f32 v[24:25], v[24:25], v[2:3] op_sel_hi:[1,0]
	v_pk_mul_f32 v[54:55], v[54:55], v[2:3] op_sel_hi:[1,0]
	v_pk_mul_f32 v[52:53], v[52:53], v[2:3] op_sel_hi:[1,0]
.Lslow_nors:
	v_add_f32_e32 v2, 0xc0c00000, v157
	s_nop 0
	v_pk_add_f32 v[116:117], v[116:117], v[2:3] op_sel_hi:[1,0] neg_lo:[0,1] neg_hi:[0,1]
	v_pk_add_f32 v[118:119], v[118:119], v[2:3] op_sel_hi:[1,0] neg_lo:[0,1] neg_hi:[0,1]
	v_pk_add_f32 v[108:109], v[108:109], v[2:3] op_sel_hi:[1,0] neg_lo:[0,1] neg_hi:[0,1]
	v_pk_add_f32 v[110:111], v[110:111], v[2:3] op_sel_hi:[1,0] neg_lo:[0,1] neg_hi:[0,1]
	v_pk_add_f32 v[96:97], v[96:97], v[2:3] op_sel_hi:[1,0] neg_lo:[0,1] neg_hi:[0,1]
	v_pk_add_f32 v[98:99], v[98:99], v[2:3] op_sel_hi:[1,0] neg_lo:[0,1] neg_hi:[0,1]
	v_pk_add_f32 v[100:101], v[100:101], v[2:3] op_sel_hi:[1,0] neg_lo:[0,1] neg_hi:[0,1]
	v_pk_add_f32 v[102:103], v[102:103], v[2:3] op_sel_hi:[1,0] neg_lo:[0,1] neg_hi:[0,1]
	v_pk_add_f32 v[112:113], v[112:113], v[2:3] op_sel_hi:[1,0] neg_lo:[0,1] neg_hi:[0,1]
	v_pk_add_f32 v[114:115], v[114:115], v[2:3] op_sel_hi:[1,0] neg_lo:[0,1] neg_hi:[0,1]
	v_pk_add_f32 v[104:105], v[104:105], v[2:3] op_sel_hi:[1,0] neg_lo:[0,1] neg_hi:[0,1]
	v_pk_add_f32 v[106:107], v[106:107], v[2:3] op_sel_hi:[1,0] neg_lo:[0,1] neg_hi:[0,1]
	v_pk_add_f32 v[92:93], v[92:93], v[2:3] op_sel_hi:[1,0] neg_lo:[0,1] neg_hi:[0,1]
	v_pk_add_f32 v[94:95], v[94:95], v[2:3] op_sel_hi:[1,0] neg_lo:[0,1] neg_hi:[0,1]
	v_pk_add_f32 v[88:89], v[88:89], v[2:3] op_sel_hi:[1,0] neg_lo:[0,1] neg_hi:[0,1]
	v_pk_add_f32 v[90:91], v[90:91], v[2:3] op_sel_hi:[1,0] neg_lo:[0,1] neg_hi:[0,1]
	s_branch .Lsel_fast_exp
